# out-proj l0 epilogue (EpiRes f32): residual rows fetched 16 loads in flight with counted vmcnt instead of 16 serialized round trips
# speedup vs baseline: 1.0060x; 1.0060x over previous
; __device__ __forceinline__ unsigned cvt_pk(float lo, float hi) { unsigned r; asm volatile("v_cvt_pk_bf16_f32 %0, %1, %2" : "=v"(r) : "v"(lo), "v"(hi)); return r; }
;     __device__ __forceinline__ void operator()(const Acc& acc, const Unit& u, int wr, int wc, int fr, int fq) const {
;         const bool isc = u.pm == 8;
;         const size_t rb = isc ? (size_t)u.pb * TC : (size_t)u.pb * TL + u.pm * 256;
;         const float* in = (isc ? inC : inL) + rb * DM; const float* gp = gate + (isc ? 32 : u.pb) * 6144;
;         const int col0 = u.pn * 256 + wc * 32 + 8 * fq; const size_t Rg = (size_t)u.pb * NT + u.pm * 256;
;         f32x4 gv[2][2];
; #pragma unroll
;         for (int bj = 0; bj < 2; ++bj)
; #pragma unroll
;             for (int n = 0; n < 2; ++n) gv[bj][n] = *(const f32x4*)(gp + col0 + bj * 128 + n * 4);
; #pragma unroll
;         for (int ai = 0; ai < 2; ++ai)
; #pragma unroll
;             for (int m = 0; m < 4; ++m) { const int rl = ai * 128 + wr * 64 + m * 16 + fr; const size_t off = (size_t)rl * DM + col0; const size_t boff = (Rg + rl) * DM + col0;
; #pragma unroll
;                 for (int bj = 0; bj < 2; ++bj) { f32x4 x0, x1;
;                     if (INF32) { x0 = *(const f32x4*)(in + off + bj * 128); x1 = *(const f32x4*)(in + off + bj * 128 + 4); }
;                     else { const u32x4 q = *(const u32x4*)(inB + boff + bj * 128); x0 = (f32x4){bflo(q.x), bfhi(q.x), bflo(q.y), bfhi(q.y)}; x1 = (f32x4){bflo(q.z), bfhi(q.z), bflo(q.w), bfhi(q.w)}; }
;                     x0 = x0 + gv[bj][0] * acc[ai][bj][m][0]; x1 = x1 + gv[bj][1] * acc[ai][bj][m][1];
;                     u32x4 w; w.x = cvt_pk(x0[0], x0[1]); w.y = cvt_pk(x0[2], x0[3]); w.z = cvt_pk(x1[0], x1[1]); w.w = cvt_pk(x1[2], x1[3]); *(u32x4*)(outB + boff + bj * 128) = w; } }
.LBB0_910:
	s_mul_i32 s15, s22, 0x1800
	s_and_b64 s[42:43], s[42:43], exec
	s_cselect_b32 s42, 0x30000, s15
	s_ashr_i32 s43, s42, 31
	s_lshl_b64 s[38:39], s[38:39], 12
	s_add_u32 s38, s44, s38
	s_addc_u32 s39, s45, s39
	s_lshl_b64 s[42:43], s[42:43], 2
	s_add_u32 s42, s61, s42
	s_addc_u32 s43, s66, s43
	s_lshl_b32 s15, s24, 8
	v_ashrrev_i32_e32 v131, 1, v130
	v_and_b32_e32 v131, -8, v131
	s_or_b32 s15, s15, s68
	v_add_u32_e32 v132, s15, v131
	v_ashrrev_i32_e32 v133, 31, v132
	v_and_or_b32 v164, v130, 15, s67
	v_lshlrev_b64 v[134:135], 2, v[132:133]
	v_ashrrev_i32_e32 v165, 31, v164
	v_lshl_add_u64 v[162:163], s[38:39], 0, v[134:135]
	v_lshlrev_b64 v[130:131], 12, v[164:165]
	v_lshl_add_u64 v[182:183], v[162:163], 0, v[130:131]
	v_lshl_add_u64 v[142:143], s[42:43], 0, v[134:135]
	s_mul_i32 s17, s22, 0x900
	s_mul_hi_i32 s15, s22, 0x900
	s_add_u32 s4, s4, s17
	s_addc_u32 s5, s5, s15
	v_lshl_add_u64 v[130:131], s[4:5], 0, v[164:165]
	v_lshlrev_b64 v[174:175], 11, v[130:131]
	v_lshlrev_b64 v[166:167], 1, v[132:133]
	v_lshl_add_u64 v[174:175], s[28:29], 0, v[174:175]
	v_lshl_add_u64 v[174:175], v[174:175], 0, v[166:167]
	global_load_dwordx4 v[138:141], v[142:143], off
	global_load_dwordx4 v[134:137], v[142:143], off offset:16
	global_load_dwordx4 v[130:133], v[142:143], off offset:528
	s_nop 0
	global_load_dwordx4 v[142:145], v[142:143], off offset:512
	s_and_b64 vcc, exec, s[2:3]
	s_mov_b64 s[2:3], -1
	global_load_dwordx4 v[184:187], v[182:183], off
	global_load_dwordx4 v[188:191], v[182:183], off offset:16
	global_load_dwordx4 v[192:195], v[182:183], off offset:512
	global_load_dwordx4 v[196:199], v[182:183], off offset:528
	s_mov_b64 s[98:99], 0x10000
	v_lshl_add_u64 v[176:177], v[182:183], 0, s[98:99]
	global_load_dwordx4 v[200:203], v[176:177], off
	global_load_dwordx4 v[204:207], v[176:177], off offset:16
	global_load_dwordx4 v[208:211], v[176:177], off offset:512
	global_load_dwordx4 v[212:215], v[176:177], off offset:528
	s_mov_b64 s[98:99], 0x20000
	v_lshl_add_u64 v[176:177], v[182:183], 0, s[98:99]
	global_load_dwordx4 v[216:219], v[176:177], off
	global_load_dwordx4 v[220:223], v[176:177], off offset:16
	global_load_dwordx4 v[224:227], v[176:177], off offset:512
	global_load_dwordx4 v[228:231], v[176:177], off offset:528
	s_mov_b64 s[98:99], 0x30000
	v_lshl_add_u64 v[176:177], v[182:183], 0, s[98:99]
	global_load_dwordx4 v[232:235], v[176:177], off
	global_load_dwordx4 v[236:239], v[176:177], off offset:16
	global_load_dwordx4 v[240:243], v[176:177], off offset:512
	global_load_dwordx4 v[244:247], v[176:177], off offset:528
	s_waitcnt vmcnt(14)
	v_pk_fma_f32 v[126:127], v[126:127], v[138:139], v[184:185]
	v_pk_fma_f32 v[128:129], v[128:129], v[140:141], v[186:187]
	v_pk_fma_f32 v[122:123], v[122:123], v[134:135], v[188:189]
	v_pk_fma_f32 v[124:125], v[124:125], v[136:137], v[190:191]
	v_cvt_pk_bf16_f32 v126, v126, v127
	v_cvt_pk_bf16_f32 v127, v128, v129
	v_cvt_pk_bf16_f32 v128, v122, v123
	v_cvt_pk_bf16_f32 v129, v124, v125
	global_store_dwordx4 v[174:175], v[126:129], off
	s_waitcnt vmcnt(13)
	v_pk_fma_f32 v[118:119], v[118:119], v[142:143], v[192:193]
	v_pk_fma_f32 v[120:121], v[120:121], v[144:145], v[194:195]
	v_pk_fma_f32 v[114:115], v[114:115], v[130:131], v[196:197]
	v_pk_fma_f32 v[116:117], v[116:117], v[132:133], v[198:199]
	v_cvt_pk_bf16_f32 v118, v118, v119
	v_cvt_pk_bf16_f32 v119, v120, v121
	v_cvt_pk_bf16_f32 v120, v114, v115
	v_cvt_pk_bf16_f32 v121, v116, v117
	global_store_dwordx4 v[174:175], v[118:121], off offset:256
	s_mov_b64 s[98:99], 0x80000
	v_lshl_add_u64 v[176:177], v[182:183], 0, s[98:99]
	global_load_dwordx4 v[184:187], v[176:177], off
	global_load_dwordx4 v[188:191], v[176:177], off offset:16
	global_load_dwordx4 v[192:195], v[176:177], off offset:512
	global_load_dwordx4 v[196:199], v[176:177], off offset:528
	s_mov_b64 s[100:101], 0x8000
	v_lshl_add_u64 v[178:179], v[174:175], 0, s[100:101]
	s_waitcnt vmcnt(16)
	v_pk_fma_f32 v[110:111], v[110:111], v[138:139], v[200:201]
	v_pk_fma_f32 v[112:113], v[112:113], v[140:141], v[202:203]
	v_pk_fma_f32 v[106:107], v[106:107], v[134:135], v[204:205]
	v_pk_fma_f32 v[108:109], v[108:109], v[136:137], v[206:207]
	v_cvt_pk_bf16_f32 v110, v110, v111
	v_cvt_pk_bf16_f32 v111, v112, v113
	v_cvt_pk_bf16_f32 v112, v106, v107
	v_cvt_pk_bf16_f32 v113, v108, v109
	global_store_dwordx4 v[178:179], v[110:113], off
	s_waitcnt vmcnt(15)
	v_pk_fma_f32 v[102:103], v[102:103], v[142:143], v[208:209]
	v_pk_fma_f32 v[104:105], v[104:105], v[144:145], v[210:211]
	v_pk_fma_f32 v[98:99], v[98:99], v[130:131], v[212:213]
	v_pk_fma_f32 v[100:101], v[100:101], v[132:133], v[214:215]
	v_cvt_pk_bf16_f32 v102, v102, v103
	v_cvt_pk_bf16_f32 v103, v104, v105
	v_cvt_pk_bf16_f32 v104, v98, v99
	v_cvt_pk_bf16_f32 v105, v100, v101
	global_store_dwordx4 v[178:179], v[102:105], off offset:256
	s_mov_b64 s[98:99], 0x90000
	v_lshl_add_u64 v[176:177], v[182:183], 0, s[98:99]
	global_load_dwordx4 v[200:203], v[176:177], off
	global_load_dwordx4 v[204:207], v[176:177], off offset:16
	global_load_dwordx4 v[208:211], v[176:177], off offset:512
	global_load_dwordx4 v[212:215], v[176:177], off offset:528
	s_mov_b64 s[100:101], 0x10000
	v_lshl_add_u64 v[178:179], v[174:175], 0, s[100:101]
	s_waitcnt vmcnt(18)
	v_pk_fma_f32 v[94:95], v[94:95], v[138:139], v[216:217]
	v_pk_fma_f32 v[96:97], v[96:97], v[140:141], v[218:219]
	v_pk_fma_f32 v[90:91], v[90:91], v[134:135], v[220:221]
	v_pk_fma_f32 v[92:93], v[92:93], v[136:137], v[222:223]
	v_cvt_pk_bf16_f32 v94, v94, v95
	v_cvt_pk_bf16_f32 v95, v96, v97
	v_cvt_pk_bf16_f32 v96, v90, v91
	v_cvt_pk_bf16_f32 v97, v92, v93
	global_store_dwordx4 v[178:179], v[94:97], off
	s_waitcnt vmcnt(17)
; __device__ __forceinline__ unsigned cvt_pk(float lo, float hi) { unsigned r; asm volatile("v_cvt_pk_bf16_f32 %0, %1, %2" : "=v"(r) : "v"(lo), "v"(hi)); return r; }
;     __device__ __forceinline__ void operator()(const Acc& acc, const Unit& u, int wr, int wc, int fr, int fq) const {
;     ...
; #pragma unroll
;         for (int ai = 0; ai < 2; ++ai)
; #pragma unroll
;             for (int m = 0; m < 4; ++m) { const int rl = ai * 128 + wr * 64 + m * 16 + fr; const size_t off = (size_t)rl * DM + col0; const size_t boff = (Rg + rl) * DM + col0;
; #pragma unroll
;                 for (int bj = 0; bj < 2; ++bj) { f32x4 x0, x1;
;                     if (INF32) { x0 = *(const f32x4*)(in + off + bj * 128); x1 = *(const f32x4*)(in + off + bj * 128 + 4); }
;                     else { const u32x4 q = *(const u32x4*)(inB + boff + bj * 128); x0 = (f32x4){bflo(q.x), bfhi(q.x), bflo(q.y), bfhi(q.y)}; x1 = (f32x4){bflo(q.z), bfhi(q.z), bflo(q.w), bfhi(q.w)}; }
;                     x0 = x0 + gv[bj][0] * acc[ai][bj][m][0]; x1 = x1 + gv[bj][1] * acc[ai][bj][m][1];
;                     u32x4 w; w.x = cvt_pk(x0[0], x0[1]); w.y = cvt_pk(x0[2], x0[3]); w.z = cvt_pk(x1[0], x1[1]); w.w = cvt_pk(x1[2], x1[3]); *(u32x4*)(outB + boff + bj * 128) = w; } }
;     }
	v_pk_fma_f32 v[86:87], v[86:87], v[142:143], v[224:225]
	v_pk_fma_f32 v[88:89], v[88:89], v[144:145], v[226:227]
	v_pk_fma_f32 v[82:83], v[82:83], v[130:131], v[228:229]
	v_pk_fma_f32 v[84:85], v[84:85], v[132:133], v[230:231]
	v_cvt_pk_bf16_f32 v86, v86, v87
	v_cvt_pk_bf16_f32 v87, v88, v89
	v_cvt_pk_bf16_f32 v88, v82, v83
	v_cvt_pk_bf16_f32 v89, v84, v85
	global_store_dwordx4 v[178:179], v[86:89], off offset:256
	s_mov_b64 s[98:99], 0xa0000
	v_lshl_add_u64 v[176:177], v[182:183], 0, s[98:99]
	global_load_dwordx4 v[216:219], v[176:177], off
	global_load_dwordx4 v[220:223], v[176:177], off offset:16
	global_load_dwordx4 v[224:227], v[176:177], off offset:512
	global_load_dwordx4 v[228:231], v[176:177], off offset:528
	s_mov_b64 s[100:101], 0x18000
	v_lshl_add_u64 v[178:179], v[174:175], 0, s[100:101]
	s_waitcnt vmcnt(20)
	v_pk_fma_f32 v[78:79], v[78:79], v[138:139], v[232:233]
	v_pk_fma_f32 v[80:81], v[80:81], v[140:141], v[234:235]
	v_pk_fma_f32 v[74:75], v[74:75], v[134:135], v[236:237]
	v_pk_fma_f32 v[76:77], v[76:77], v[136:137], v[238:239]
	v_cvt_pk_bf16_f32 v78, v78, v79
	v_cvt_pk_bf16_f32 v79, v80, v81
	v_cvt_pk_bf16_f32 v80, v74, v75
	v_cvt_pk_bf16_f32 v81, v76, v77
	global_store_dwordx4 v[178:179], v[78:81], off
	s_waitcnt vmcnt(19)
	v_pk_fma_f32 v[70:71], v[70:71], v[142:143], v[240:241]
	v_pk_fma_f32 v[72:73], v[72:73], v[144:145], v[242:243]
	v_pk_fma_f32 v[66:67], v[66:67], v[130:131], v[244:245]
	v_pk_fma_f32 v[68:69], v[68:69], v[132:133], v[246:247]
	v_cvt_pk_bf16_f32 v70, v70, v71
	v_cvt_pk_bf16_f32 v71, v72, v73
	v_cvt_pk_bf16_f32 v72, v66, v67
	v_cvt_pk_bf16_f32 v73, v68, v69
	global_store_dwordx4 v[178:179], v[70:73], off offset:256
	s_mov_b64 s[98:99], 0xb0000
	v_lshl_add_u64 v[176:177], v[182:183], 0, s[98:99]
	global_load_dwordx4 v[232:235], v[176:177], off
	global_load_dwordx4 v[236:239], v[176:177], off offset:16
	global_load_dwordx4 v[240:243], v[176:177], off offset:512
	global_load_dwordx4 v[244:247], v[176:177], off offset:528
	s_mov_b64 s[100:101], 0x40000
	v_lshl_add_u64 v[178:179], v[174:175], 0, s[100:101]
	s_waitcnt vmcnt(20)
	v_pk_fma_f32 v[62:63], v[62:63], v[138:139], v[184:185]
	v_pk_fma_f32 v[64:65], v[64:65], v[140:141], v[186:187]
	v_pk_fma_f32 v[58:59], v[58:59], v[134:135], v[188:189]
	v_pk_fma_f32 v[60:61], v[60:61], v[136:137], v[190:191]
	v_cvt_pk_bf16_f32 v62, v62, v63
	v_cvt_pk_bf16_f32 v63, v64, v65
	v_cvt_pk_bf16_f32 v64, v58, v59
	v_cvt_pk_bf16_f32 v65, v60, v61
	global_store_dwordx4 v[178:179], v[62:65], off
	s_waitcnt vmcnt(19)
	v_pk_fma_f32 v[54:55], v[54:55], v[142:143], v[192:193]
	v_pk_fma_f32 v[56:57], v[56:57], v[144:145], v[194:195]
	v_pk_fma_f32 v[50:51], v[50:51], v[130:131], v[196:197]
	v_pk_fma_f32 v[52:53], v[52:53], v[132:133], v[198:199]
	v_cvt_pk_bf16_f32 v54, v54, v55
	v_cvt_pk_bf16_f32 v55, v56, v57
	v_cvt_pk_bf16_f32 v56, v50, v51
	v_cvt_pk_bf16_f32 v57, v52, v53
	global_store_dwordx4 v[178:179], v[54:57], off offset:256
	s_mov_b64 s[100:101], 0x48000
	v_lshl_add_u64 v[178:179], v[174:175], 0, s[100:101]
	s_waitcnt vmcnt(16)
	v_pk_fma_f32 v[46:47], v[46:47], v[138:139], v[200:201]
	v_pk_fma_f32 v[48:49], v[48:49], v[140:141], v[202:203]
	v_pk_fma_f32 v[42:43], v[42:43], v[134:135], v[204:205]
	v_pk_fma_f32 v[44:45], v[44:45], v[136:137], v[206:207]
	v_cvt_pk_bf16_f32 v46, v46, v47
	v_cvt_pk_bf16_f32 v47, v48, v49
	v_cvt_pk_bf16_f32 v48, v42, v43
	v_cvt_pk_bf16_f32 v49, v44, v45
	global_store_dwordx4 v[178:179], v[46:49], off
	s_waitcnt vmcnt(15)
	v_pk_fma_f32 v[38:39], v[38:39], v[142:143], v[208:209]
	v_pk_fma_f32 v[40:41], v[40:41], v[144:145], v[210:211]
	v_pk_fma_f32 v[34:35], v[34:35], v[130:131], v[212:213]
	v_pk_fma_f32 v[36:37], v[36:37], v[132:133], v[214:215]
	v_cvt_pk_bf16_f32 v38, v38, v39
	v_cvt_pk_bf16_f32 v39, v40, v41
	v_cvt_pk_bf16_f32 v40, v34, v35
	v_cvt_pk_bf16_f32 v41, v36, v37
	global_store_dwordx4 v[178:179], v[38:41], off offset:256
	s_mov_b64 s[100:101], 0x50000
	v_lshl_add_u64 v[178:179], v[174:175], 0, s[100:101]
	s_waitcnt vmcnt(12)
	v_pk_fma_f32 v[30:31], v[30:31], v[138:139], v[216:217]
	v_pk_fma_f32 v[32:33], v[32:33], v[140:141], v[218:219]
	v_pk_fma_f32 v[26:27], v[26:27], v[134:135], v[220:221]
	v_pk_fma_f32 v[28:29], v[28:29], v[136:137], v[222:223]
	v_cvt_pk_bf16_f32 v30, v30, v31
	v_cvt_pk_bf16_f32 v31, v32, v33
	v_cvt_pk_bf16_f32 v32, v26, v27
	v_cvt_pk_bf16_f32 v33, v28, v29
	global_store_dwordx4 v[178:179], v[30:33], off
	s_waitcnt vmcnt(11)
	v_pk_fma_f32 v[22:23], v[22:23], v[142:143], v[224:225]
	v_pk_fma_f32 v[24:25], v[24:25], v[144:145], v[226:227]
	v_pk_fma_f32 v[18:19], v[18:19], v[130:131], v[228:229]
	v_pk_fma_f32 v[20:21], v[20:21], v[132:133], v[230:231]
	v_cvt_pk_bf16_f32 v22, v22, v23
	v_cvt_pk_bf16_f32 v23, v24, v25
	v_cvt_pk_bf16_f32 v24, v18, v19
	v_cvt_pk_bf16_f32 v25, v20, v21
	global_store_dwordx4 v[178:179], v[22:25], off offset:256
	s_mov_b64 s[100:101], 0x58000
	v_lshl_add_u64 v[178:179], v[174:175], 0, s[100:101]
	s_waitcnt vmcnt(8)
	v_pk_fma_f32 v[14:15], v[14:15], v[138:139], v[232:233]
	v_pk_fma_f32 v[16:17], v[16:17], v[140:141], v[234:235]
	v_pk_fma_f32 v[10:11], v[10:11], v[134:135], v[236:237]
	v_pk_fma_f32 v[12:13], v[12:13], v[136:137], v[238:239]
	v_cvt_pk_bf16_f32 v14, v14, v15
	v_cvt_pk_bf16_f32 v15, v16, v17
	v_cvt_pk_bf16_f32 v16, v10, v11
	v_cvt_pk_bf16_f32 v17, v12, v13
	global_store_dwordx4 v[178:179], v[14:17], off
	s_waitcnt vmcnt(7)
	v_pk_fma_f32 v[6:7], v[6:7], v[142:143], v[240:241]
	v_pk_fma_f32 v[8:9], v[8:9], v[144:145], v[242:243]
	v_pk_fma_f32 v[2:3], v[2:3], v[130:131], v[244:245]
	v_pk_fma_f32 v[4:5], v[4:5], v[132:133], v[246:247]
	v_cvt_pk_bf16_f32 v6, v6, v7
	v_cvt_pk_bf16_f32 v7, v8, v9
	v_cvt_pk_bf16_f32 v8, v2, v3
	v_cvt_pk_bf16_f32 v9, v4, v5
	global_store_dwordx4 v[178:179], v[6:9], off offset:256
	s_cbranch_vccnz .LBB0_897
	s_andn2_b64 vcc, exec, s[8:9]
	s_cbranch_vccnz .LBB0_896
	s_barrier
	s_branch .LBB0_896

; #define LAS __attribute__((address_space(3)))
; __global__ void __launch_bounds__(512, 2) mk_fwd(Args args) {
;     extern __shared__ __attribute__((aligned(16))) unsigned char lds_raw[];
;     LAS unsigned char* lds = (LAS unsigned char*)lds_raw;
	.amdhsa_kernel _Z6mk_fwd4Args
		.amdhsa_group_segment_fixed_size 0
		.amdhsa_private_segment_fixed_size 0
		.amdhsa_kernarg_size 440
		.amdhsa_user_sgpr_count 2
		.amdhsa_user_sgpr_dispatch_ptr 0
		.amdhsa_user_sgpr_queue_ptr 0
		.amdhsa_user_sgpr_kernarg_segment_ptr 1
		.amdhsa_user_sgpr_dispatch_id 0
		.amdhsa_user_sgpr_kernarg_preload_length 0
		.amdhsa_user_sgpr_kernarg_preload_offset 0
		.amdhsa_user_sgpr_private_segment_size 0
		.amdhsa_uses_dynamic_stack 0
		.amdhsa_enable_private_segment 0
		.amdhsa_system_sgpr_workgroup_id_x 1
		.amdhsa_system_sgpr_workgroup_id_y 0
		.amdhsa_system_sgpr_workgroup_id_z 0
		.amdhsa_system_sgpr_workgroup_info 0
		.amdhsa_system_vgpr_workitem_id 2
		.amdhsa_next_free_vgpr 249
		.amdhsa_next_free_sgpr 102
		.amdhsa_accum_offset 252
		.amdhsa_reserve_vcc 1
		.amdhsa_float_round_mode_32 0
		.amdhsa_float_round_mode_16_64 0
		.amdhsa_float_denorm_mode_32 3
		.amdhsa_float_denorm_mode_16_64 3
		.amdhsa_dx10_clamp 1
		.amdhsa_ieee_mode 1
		.amdhsa_fp16_overflow 0
		.amdhsa_tg_split 0
		.amdhsa_exception_fp_ieee_invalid_op 0
		.amdhsa_exception_fp_denorm_src 0
		.amdhsa_exception_fp_ieee_div_zero 0
		.amdhsa_exception_fp_ieee_overflow 0
		.amdhsa_exception_fp_ieee_underflow 0
		.amdhsa_exception_fp_ieee_inexact 0
		.amdhsa_exception_int_div_zero 0
	.end_amdhsa_kernel

; #define LAS __attribute__((address_space(3)))
; __global__ void __launch_bounds__(512, 2) mk_fwd(Args args) {
;     extern __shared__ __attribute__((aligned(16))) unsigned char lds_raw[];
;     LAS unsigned char* lds = (LAS unsigned char*)lds_raw;
amdhsa.kernels:
  - .agpr_count:     0
    .args:
      - .offset:         0
        .size:           184
        .value_kind:     by_value
      - .offset:         184
        .size:           4
        .value_kind:     hidden_block_count_x
      - .offset:         188
        .size:           4
        .value_kind:     hidden_block_count_y
      - .offset:         192
        .size:           4
        .value_kind:     hidden_block_count_z
      - .offset:         196
        .size:           2
        .value_kind:     hidden_group_size_x
      - .offset:         198
        .size:           2
        .value_kind:     hidden_group_size_y
      - .offset:         200
        .size:           2
        .value_kind:     hidden_group_size_z
      - .offset:         202
        .size:           2
        .value_kind:     hidden_remainder_x
      - .offset:         204
        .size:           2
        .value_kind:     hidden_remainder_y
      - .offset:         206
        .size:           2
        .value_kind:     hidden_remainder_z
      - .offset:         224
        .size:           8
        .value_kind:     hidden_global_offset_x
      - .offset:         232
        .size:           8
        .value_kind:     hidden_global_offset_y
      - .offset:         240
        .size:           8
        .value_kind:     hidden_global_offset_z
      - .offset:         248
        .size:           2
        .value_kind:     hidden_grid_dims
      - .offset:         272
        .size:           8
        .value_kind:     hidden_multigrid_sync_arg
      - .offset:         304
        .size:           4
        .value_kind:     hidden_dynamic_lds_size
    .group_segment_fixed_size: 0
    .kernarg_segment_align: 8
    .kernarg_segment_size: 440
    .language:       OpenCL C
    .language_version:
      - 2
      - 0
    .max_flat_workgroup_size: 512
    .name:           _Z6mk_fwd4Args
    .private_segment_fixed_size: 0
    .sgpr_count:     108
    .sgpr_spill_count: 19
    .symbol:         _Z6mk_fwd4Args.kd
    .uniform_work_group_size: 1
    .uses_dynamic_stack: false
    .vgpr_count:     249
    .vgpr_spill_count: 0
    .wavefront_size: 64
